# y-GEMM gate-rescale hook: second load batch issued before the first wait (counted vmcnt 8)
# baseline (speedup 1.0000x reference)
.LBB0_810:
	s_andn2_b64 vcc, exec, s[36:37]
	s_cbranch_vccnz .LBB0_807
	s_cmpk_eq_i32 s34, 0x200
	s_cselect_b32 s36, 0, 0x80
	s_cselect_b32 s38, s82, 0x100
	s_add_i32 s36, s36, s24
	s_ashr_i32 s37, s36, 31
	s_lshl_b64 s[36:37], s[36:37], 19
	s_add_u32 s36, s29, s36
	v_mov_b32_e32 v130, v218
	s_addc_u32 s37, s61, s37
	s_add_i32 s38, s38, s24
	s_ashr_i32 s39, s38, 31
	v_lshlrev_b32_e32 v130, 4, v130
	s_lshl_b64 s[38:39], s[38:39], 19
	v_and_b32_e32 v130, 0x3f0, v130
	s_add_u32 s38, s29, s38
	s_addc_u32 s39, s61, s39
	global_load_dwordx4 v[230:233], v130, s[36:37]
	global_load_dwordx4 v[234:237], v130, s[38:39]
	global_load_dwordx4 v[182:185], v130, s[36:37] offset:1024
	global_load_dwordx4 v[178:181], v130, s[38:39] offset:1024
	global_load_dwordx4 v[174:177], v130, s[36:37] offset:2048
	global_load_dwordx4 v[170:173], v130, s[38:39] offset:2048
	global_load_dwordx4 v[166:169], v130, s[36:37] offset:3072
	global_load_dwordx4 v[162:165], v130, s[38:39] offset:3072
	v_mov_b32_e32 v131, v0
	v_lshl_add_u64 v[212:213], s[36:37], 0, v[130:131]
	v_add_co_u32_e32 v134, vcc, s33, v212
	v_lshl_add_u64 v[210:211], s[38:39], 0, v[130:131]
	s_nop 0
	v_addc_co_u32_e32 v135, vcc, 0, v213, vcc
	v_add_co_u32_e32 v214, vcc, s0, v212
	s_nop 1
	v_addc_co_u32_e32 v215, vcc, 0, v213, vcc
	global_load_dwordx4 v[158:161], v[214:215], off offset:-4096
	v_add_co_u32_e32 v136, vcc, s33, v210
	s_nop 1
	v_addc_co_u32_e32 v137, vcc, 0, v211, vcc
	v_add_co_u32_e32 v216, vcc, s0, v210
	s_nop 1
	v_addc_co_u32_e32 v217, vcc, 0, v211, vcc
	global_load_dwordx4 v[150:153], v[216:217], off offset:-4096
	global_load_dwordx4 v[154:157], v[134:135], off offset:1024
	global_load_dwordx4 v[146:149], v[136:137], off offset:1024
	global_load_dwordx4 v[138:141], v[134:135], off offset:2048
	global_load_dwordx4 v[130:133], v[136:137], off offset:2048
	global_load_dwordx4 v[142:145], v[134:135], off offset:3072
	s_nop 0
	global_load_dwordx4 v[134:137], v[136:137], off offset:3072
	s_waitcnt vmcnt(8)
	v_lshlrev_b32_e32 v196, 16, v230
	v_and_b32_e32 v197, 0xffff0000, v230
	v_rcp_f32_e32 v196, v196
	v_rcp_f32_e32 v197, v197
	v_lshlrev_b32_e32 v198, 16, v232
	v_and_b32_e32 v199, 0xffff0000, v232
	v_rcp_f32_e32 v198, v198
	v_rcp_f32_e32 v199, v199
	v_lshlrev_b32_e32 v220, 16, v234
	v_and_b32_e32 v221, 0xffff0000, v234
	v_pk_mul_f32 v[196:197], v[196:197], v[220:221]
	v_lshlrev_b32_e32 v222, 16, v231
	v_pk_mul_f32 v[126:127], v[126:127], v[196:197]
	v_lshlrev_b32_e32 v196, 16, v236
	v_and_b32_e32 v197, 0xffff0000, v236
	v_and_b32_e32 v223, 0xffff0000, v231
	v_pk_mul_f32 v[196:197], v[198:199], v[196:197]
	v_lshlrev_b32_e32 v229, 16, v233
	v_pk_mul_f32 v[122:123], v[122:123], v[196:197]
	v_rcp_f32_e32 v196, v222
	v_rcp_f32_e32 v197, v223
	v_and_b32_e32 v230, 0xffff0000, v233
	v_rcp_f32_e32 v198, v229
	v_rcp_f32_e32 v199, v230
	v_lshlrev_b32_e32 v220, 16, v235
	v_and_b32_e32 v221, 0xffff0000, v235
	v_pk_mul_f32 v[196:197], v[196:197], v[220:221]
	v_and_b32_e32 v220, 0xffff0000, v184
	v_pk_mul_f32 v[128:129], v[128:129], v[196:197]
	v_lshlrev_b32_e32 v196, 16, v237
	v_and_b32_e32 v197, 0xffff0000, v237
	v_pk_mul_f32 v[196:197], v[198:199], v[196:197]
	v_lshlrev_b32_e32 v198, 16, v183
	v_pk_mul_f32 v[124:125], v[124:125], v[196:197]
	v_lshlrev_b32_e32 v196, 16, v182
	v_and_b32_e32 v197, 0xffff0000, v182
	v_and_b32_e32 v199, 0xffff0000, v183
	v_lshlrev_b32_e32 v183, 16, v184
	v_rcp_f32_e32 v182, v196
	v_rcp_f32_e32 v184, v183
	v_rcp_f32_e32 v183, v197
	v_lshlrev_b32_e32 v221, 16, v185
	v_and_b32_e32 v222, 0xffff0000, v185
	v_rcp_f32_e32 v185, v220
	v_lshlrev_b32_e32 v196, 16, v178
	v_and_b32_e32 v197, 0xffff0000, v178
	v_pk_mul_f32 v[182:183], v[182:183], v[196:197]
	v_rcp_f32_e32 v178, v221
	v_pk_mul_f32 v[118:119], v[118:119], v[182:183]
	v_lshlrev_b32_e32 v182, 16, v180
	v_and_b32_e32 v183, 0xffff0000, v180
	v_pk_mul_f32 v[182:183], v[184:185], v[182:183]
	v_lshlrev_b32_e32 v184, 16, v179
	v_and_b32_e32 v185, 0xffff0000, v179
	v_rcp_f32_e32 v179, v222
	v_pk_mul_f32 v[114:115], v[114:115], v[182:183]
	v_rcp_f32_e32 v182, v198
	v_rcp_f32_e32 v183, v199
	v_lshlrev_b32_e32 v180, 16, v181
	v_and_b32_e32 v181, 0xffff0000, v181
	v_pk_mul_f32 v[178:179], v[178:179], v[180:181]
	v_pk_mul_f32 v[182:183], v[182:183], v[184:185]
	v_pk_mul_f32 v[116:117], v[116:117], v[178:179]
	v_lshlrev_b32_e32 v178, 16, v174
	v_and_b32_e32 v179, 0xffff0000, v174
	v_lshlrev_b32_e32 v180, 16, v175
	v_and_b32_e32 v181, 0xffff0000, v175
	v_lshlrev_b32_e32 v175, 16, v176
	v_pk_mul_f32 v[120:121], v[120:121], v[182:183]
	v_and_b32_e32 v182, 0xffff0000, v176
	v_rcp_f32_e32 v174, v178
	v_rcp_f32_e32 v176, v175
	v_rcp_f32_e32 v175, v179
	v_lshlrev_b32_e32 v183, 16, v177
	v_and_b32_e32 v184, 0xffff0000, v177
	v_rcp_f32_e32 v177, v182
	v_lshlrev_b32_e32 v178, 16, v170
	v_and_b32_e32 v179, 0xffff0000, v170
	v_pk_mul_f32 v[174:175], v[174:175], v[178:179]
	v_rcp_f32_e32 v170, v183
	v_pk_mul_f32 v[110:111], v[110:111], v[174:175]
	v_lshlrev_b32_e32 v174, 16, v172
	v_and_b32_e32 v175, 0xffff0000, v172
	v_pk_mul_f32 v[174:175], v[176:177], v[174:175]
	v_lshlrev_b32_e32 v176, 16, v171
	v_and_b32_e32 v177, 0xffff0000, v171
	v_rcp_f32_e32 v171, v184
	v_pk_mul_f32 v[106:107], v[106:107], v[174:175]
	v_rcp_f32_e32 v174, v180
	v_rcp_f32_e32 v175, v181
	v_lshlrev_b32_e32 v172, 16, v173
	v_and_b32_e32 v173, 0xffff0000, v173
	v_pk_mul_f32 v[170:171], v[170:171], v[172:173]
	v_pk_mul_f32 v[174:175], v[174:175], v[176:177]
	v_pk_mul_f32 v[108:109], v[108:109], v[170:171]
	v_lshlrev_b32_e32 v170, 16, v166
	v_and_b32_e32 v171, 0xffff0000, v166
	v_lshlrev_b32_e32 v172, 16, v167
	v_and_b32_e32 v173, 0xffff0000, v167
	v_lshlrev_b32_e32 v167, 16, v168
	v_pk_mul_f32 v[112:113], v[112:113], v[174:175]
	v_and_b32_e32 v174, 0xffff0000, v168
	v_rcp_f32_e32 v166, v170
	v_rcp_f32_e32 v168, v167
	v_rcp_f32_e32 v167, v171
	v_lshlrev_b32_e32 v175, 16, v169
	v_and_b32_e32 v176, 0xffff0000, v169
	v_rcp_f32_e32 v169, v174
	v_lshlrev_b32_e32 v170, 16, v162
	v_and_b32_e32 v171, 0xffff0000, v162
	v_pk_mul_f32 v[166:167], v[166:167], v[170:171]
	v_rcp_f32_e32 v162, v175
	v_pk_mul_f32 v[102:103], v[102:103], v[166:167]
	v_lshlrev_b32_e32 v166, 16, v164
	v_and_b32_e32 v167, 0xffff0000, v164
	v_pk_mul_f32 v[166:167], v[168:169], v[166:167]
	v_lshlrev_b32_e32 v168, 16, v163
	v_and_b32_e32 v169, 0xffff0000, v163
	v_rcp_f32_e32 v163, v176
	v_pk_mul_f32 v[98:99], v[98:99], v[166:167]
	v_rcp_f32_e32 v166, v172
	v_rcp_f32_e32 v167, v173
	v_lshlrev_b32_e32 v164, 16, v165
	v_and_b32_e32 v165, 0xffff0000, v165
	v_pk_mul_f32 v[162:163], v[162:163], v[164:165]
	v_pk_mul_f32 v[166:167], v[166:167], v[168:169]
	v_pk_mul_f32 v[100:101], v[100:101], v[162:163]
	s_waitcnt vmcnt(0)
	v_lshlrev_b32_e32 v162, 16, v158
	v_and_b32_e32 v163, 0xffff0000, v158
	v_lshlrev_b32_e32 v164, 16, v159
	v_and_b32_e32 v165, 0xffff0000, v159
	v_lshlrev_b32_e32 v159, 16, v160
	v_pk_mul_f32 v[104:105], v[104:105], v[166:167]
	v_and_b32_e32 v166, 0xffff0000, v160
	v_rcp_f32_e32 v158, v162
	v_rcp_f32_e32 v160, v159
	v_rcp_f32_e32 v159, v163
	v_lshlrev_b32_e32 v167, 16, v161
	v_and_b32_e32 v168, 0xffff0000, v161
	v_rcp_f32_e32 v161, v166
	v_lshlrev_b32_e32 v162, 16, v150
	v_and_b32_e32 v163, 0xffff0000, v150
	v_pk_mul_f32 v[158:159], v[158:159], v[162:163]
	v_rcp_f32_e32 v150, v167
	v_pk_mul_f32 v[94:95], v[94:95], v[158:159]
	v_lshlrev_b32_e32 v158, 16, v152
	v_and_b32_e32 v159, 0xffff0000, v152
	v_pk_mul_f32 v[158:159], v[160:161], v[158:159]
	v_lshlrev_b32_e32 v160, 16, v151
	v_pk_mul_f32 v[90:91], v[90:91], v[158:159]
	v_rcp_f32_e32 v158, v164
	v_rcp_f32_e32 v159, v165
	v_and_b32_e32 v161, 0xffff0000, v151
	v_rcp_f32_e32 v151, v168
	global_load_dwordx4 v[178:181], v[214:215], off
	global_load_dwordx4 v[166:169], v[216:217], off
	global_load_dwordx4 v[230:233], v[214:215], off offset:1024
	global_load_dwordx4 v[182:185], v[216:217], off offset:1024
	global_load_dwordx4 v[234:237], v[214:215], off offset:2048
	global_load_dwordx4 v[174:177], v[216:217], off offset:2048
	global_load_dwordx4 v[170:173], v[214:215], off offset:3072
	global_load_dwordx4 v[162:165], v[216:217], off offset:3072
	v_lshlrev_b32_e32 v152, 16, v153
	v_and_b32_e32 v153, 0xffff0000, v153
	v_pk_mul_f32 v[150:151], v[150:151], v[152:153]
	v_lshlrev_b32_e32 v152, 16, v156
	v_pk_mul_f32 v[92:93], v[92:93], v[150:151]
	v_lshlrev_b32_e32 v150, 16, v154
	v_and_b32_e32 v151, 0xffff0000, v154
	v_rcp_f32_e32 v150, v150
	v_rcp_f32_e32 v151, v151
	v_and_b32_e32 v153, 0xffff0000, v156
	v_pk_mul_f32 v[158:159], v[158:159], v[160:161]
	v_rcp_f32_e32 v152, v152
	v_rcp_f32_e32 v153, v153
	v_pk_mul_f32 v[96:97], v[96:97], v[158:159]
	v_lshlrev_b32_e32 v158, 16, v155
	v_and_b32_e32 v159, 0xffff0000, v155
	v_lshlrev_b32_e32 v154, 16, v146
	v_and_b32_e32 v155, 0xffff0000, v146
	v_pk_mul_f32 v[150:151], v[150:151], v[154:155]
	v_lshlrev_b32_e32 v156, 16, v157
	v_and_b32_e32 v157, 0xffff0000, v157
	v_pk_mul_f32 v[86:87], v[86:87], v[150:151]
	v_lshlrev_b32_e32 v150, 16, v148
	v_and_b32_e32 v151, 0xffff0000, v148
	v_pk_mul_f32 v[150:151], v[152:153], v[150:151]
	v_rcp_f32_e32 v146, v156
	v_lshlrev_b32_e32 v152, 16, v147
	v_and_b32_e32 v153, 0xffff0000, v147
	v_rcp_f32_e32 v147, v157
	v_pk_mul_f32 v[82:83], v[82:83], v[150:151]
	v_rcp_f32_e32 v150, v158
	v_rcp_f32_e32 v151, v159
	v_lshlrev_b32_e32 v148, 16, v149
	v_and_b32_e32 v149, 0xffff0000, v149
	v_pk_mul_f32 v[146:147], v[146:147], v[148:149]
	v_pk_mul_f32 v[150:151], v[150:151], v[152:153]
	v_pk_mul_f32 v[84:85], v[84:85], v[146:147]
	v_lshlrev_b32_e32 v146, 16, v138
	v_and_b32_e32 v147, 0xffff0000, v138
	v_lshlrev_b32_e32 v148, 16, v139
	v_and_b32_e32 v149, 0xffff0000, v139
	v_lshlrev_b32_e32 v139, 16, v140
	v_pk_mul_f32 v[88:89], v[88:89], v[150:151]
	v_and_b32_e32 v150, 0xffff0000, v140
	v_rcp_f32_e32 v138, v146
	v_rcp_f32_e32 v140, v139
	v_rcp_f32_e32 v139, v147
	v_lshlrev_b32_e32 v151, 16, v141
	v_and_b32_e32 v152, 0xffff0000, v141
	v_rcp_f32_e32 v141, v150
	v_lshlrev_b32_e32 v146, 16, v130
	v_and_b32_e32 v147, 0xffff0000, v130
	v_pk_mul_f32 v[138:139], v[138:139], v[146:147]
	v_rcp_f32_e32 v130, v151
	v_pk_mul_f32 v[78:79], v[78:79], v[138:139]
	v_lshlrev_b32_e32 v138, 16, v132
	v_and_b32_e32 v139, 0xffff0000, v132
	v_pk_mul_f32 v[138:139], v[140:141], v[138:139]
	v_lshlrev_b32_e32 v140, 16, v131
	v_and_b32_e32 v141, 0xffff0000, v131
	v_rcp_f32_e32 v131, v152
	v_lshlrev_b32_e32 v132, 16, v133
	v_and_b32_e32 v133, 0xffff0000, v133
	v_pk_mul_f32 v[74:75], v[74:75], v[138:139]
	v_rcp_f32_e32 v138, v148
	v_rcp_f32_e32 v139, v149
	v_pk_mul_f32 v[130:131], v[130:131], v[132:133]
	v_lshlrev_b32_e32 v132, 16, v144
	v_pk_mul_f32 v[76:77], v[76:77], v[130:131]
	v_lshlrev_b32_e32 v130, 16, v142
	v_and_b32_e32 v131, 0xffff0000, v142
	v_rcp_f32_e32 v130, v130
	v_rcp_f32_e32 v131, v131
	v_and_b32_e32 v133, 0xffff0000, v144
	v_pk_mul_f32 v[138:139], v[138:139], v[140:141]
	v_rcp_f32_e32 v132, v132
	v_rcp_f32_e32 v133, v133
	v_pk_mul_f32 v[80:81], v[80:81], v[138:139]
	v_lshlrev_b32_e32 v138, 16, v134
	v_and_b32_e32 v139, 0xffff0000, v134
	v_pk_mul_f32 v[130:131], v[130:131], v[138:139]
	v_lshlrev_b32_e32 v140, 16, v143
	v_pk_mul_f32 v[70:71], v[70:71], v[130:131]
	v_lshlrev_b32_e32 v130, 16, v136
	v_and_b32_e32 v131, 0xffff0000, v136
	v_and_b32_e32 v141, 0xffff0000, v143
	v_pk_mul_f32 v[130:131], v[132:133], v[130:131]
	v_lshlrev_b32_e32 v142, 16, v145
	v_pk_mul_f32 v[66:67], v[66:67], v[130:131]
	v_rcp_f32_e32 v130, v140
	v_rcp_f32_e32 v131, v141
	v_and_b32_e32 v143, 0xffff0000, v145
	v_rcp_f32_e32 v132, v142
	v_rcp_f32_e32 v133, v143
	v_lshlrev_b32_e32 v134, 16, v135
	v_and_b32_e32 v135, 0xffff0000, v135
	v_pk_mul_f32 v[130:131], v[130:131], v[134:135]
	s_waitcnt vmcnt(0)
	v_lshlrev_b32_e32 v196, 16, v178
	v_pk_mul_f32 v[72:73], v[72:73], v[130:131]
	v_lshlrev_b32_e32 v130, 16, v137
	v_and_b32_e32 v131, 0xffff0000, v137
	v_pk_mul_f32 v[130:131], v[132:133], v[130:131]
	v_and_b32_e32 v197, 0xffff0000, v178
	v_pk_mul_f32 v[68:69], v[68:69], v[130:131]
	v_add_co_u32_e32 v130, vcc, s88, v212
	v_lshlrev_b32_e32 v198, 16, v179
	s_nop 0
	v_addc_co_u32_e32 v131, vcc, 0, v213, vcc
	global_load_dwordx4 v[158:161], v[130:131], off
	v_add_co_u32_e32 v132, vcc, s88, v210
	v_and_b32_e32 v199, 0xffff0000, v179
	s_nop 0
	v_addc_co_u32_e32 v133, vcc, 0, v211, vcc
	global_load_dwordx4 v[154:157], v[132:133], off
	global_load_dwordx4 v[150:153], v[130:131], off offset:1024
	global_load_dwordx4 v[146:149], v[132:133], off offset:1024
	global_load_dwordx4 v[142:145], v[130:131], off offset:2048
	global_load_dwordx4 v[138:141], v[132:133], off offset:2048
	global_load_dwordx4 v[134:137], v[130:131], off offset:3072
	s_nop 0
	global_load_dwordx4 v[130:133], v[132:133], off offset:3072
	v_lshlrev_b32_e32 v179, 16, v180
	v_and_b32_e32 v210, 0xffff0000, v180
	v_rcp_f32_e32 v178, v196
	v_rcp_f32_e32 v180, v179
	v_rcp_f32_e32 v179, v197
	v_lshlrev_b32_e32 v211, 16, v181
	v_and_b32_e32 v212, 0xffff0000, v181
	v_rcp_f32_e32 v181, v210
	v_lshlrev_b32_e32 v196, 16, v166
	v_and_b32_e32 v197, 0xffff0000, v166
	v_pk_mul_f32 v[178:179], v[178:179], v[196:197]
	v_rcp_f32_e32 v166, v211
	v_pk_mul_f32 v[62:63], v[62:63], v[178:179]
	v_lshlrev_b32_e32 v178, 16, v168
	v_and_b32_e32 v179, 0xffff0000, v168
	v_pk_mul_f32 v[178:179], v[180:181], v[178:179]
	v_lshlrev_b32_e32 v180, 16, v167
	v_and_b32_e32 v181, 0xffff0000, v167
	v_rcp_f32_e32 v167, v212
	v_lshlrev_b32_e32 v168, 16, v169
	v_and_b32_e32 v169, 0xffff0000, v169
	v_pk_mul_f32 v[58:59], v[58:59], v[178:179]
	v_rcp_f32_e32 v178, v198
	v_rcp_f32_e32 v179, v199
	v_pk_mul_f32 v[166:167], v[166:167], v[168:169]
	v_lshlrev_b32_e32 v168, 16, v232
	v_pk_mul_f32 v[60:61], v[60:61], v[166:167]
	v_lshlrev_b32_e32 v166, 16, v230
	v_and_b32_e32 v167, 0xffff0000, v230
	v_rcp_f32_e32 v166, v166
	v_rcp_f32_e32 v167, v167
	v_and_b32_e32 v169, 0xffff0000, v232
	v_pk_mul_f32 v[178:179], v[178:179], v[180:181]
	v_rcp_f32_e32 v168, v168
	v_rcp_f32_e32 v169, v169
	v_pk_mul_f32 v[64:65], v[64:65], v[178:179]
	v_lshlrev_b32_e32 v178, 16, v182
	v_and_b32_e32 v179, 0xffff0000, v182
	v_pk_mul_f32 v[166:167], v[166:167], v[178:179]
	v_lshlrev_b32_e32 v180, 16, v231
	v_pk_mul_f32 v[54:55], v[54:55], v[166:167]
	v_lshlrev_b32_e32 v166, 16, v184
	v_and_b32_e32 v167, 0xffff0000, v184
	v_and_b32_e32 v181, 0xffff0000, v231
	v_pk_mul_f32 v[166:167], v[168:169], v[166:167]
	v_lshlrev_b32_e32 v196, 16, v233
	v_pk_mul_f32 v[50:51], v[50:51], v[166:167]
	v_rcp_f32_e32 v166, v180
	v_rcp_f32_e32 v167, v181
	v_and_b32_e32 v197, 0xffff0000, v233
	v_rcp_f32_e32 v168, v196
	v_rcp_f32_e32 v169, v197
	v_lshlrev_b32_e32 v178, 16, v183
	v_and_b32_e32 v179, 0xffff0000, v183
	v_pk_mul_f32 v[166:167], v[166:167], v[178:179]
	v_lshlrev_b32_e32 v178, 16, v174
	v_pk_mul_f32 v[56:57], v[56:57], v[166:167]
	v_lshlrev_b32_e32 v166, 16, v185
	v_and_b32_e32 v167, 0xffff0000, v185
	v_pk_mul_f32 v[166:167], v[168:169], v[166:167]
	v_lshlrev_b32_e32 v168, 16, v236
	v_pk_mul_f32 v[52:53], v[52:53], v[166:167]
	v_lshlrev_b32_e32 v166, 16, v234
	v_and_b32_e32 v167, 0xffff0000, v234
	v_rcp_f32_e32 v166, v166
	v_rcp_f32_e32 v167, v167
	v_and_b32_e32 v169, 0xffff0000, v236
	v_rcp_f32_e32 v168, v168
	v_rcp_f32_e32 v169, v169
	v_and_b32_e32 v179, 0xffff0000, v174
	v_pk_mul_f32 v[166:167], v[166:167], v[178:179]
	v_lshlrev_b32_e32 v180, 16, v235
	v_pk_mul_f32 v[46:47], v[46:47], v[166:167]
	v_lshlrev_b32_e32 v166, 16, v176
	v_and_b32_e32 v167, 0xffff0000, v176
	v_and_b32_e32 v181, 0xffff0000, v235
	v_pk_mul_f32 v[166:167], v[168:169], v[166:167]
	v_lshlrev_b32_e32 v182, 16, v237
	v_pk_mul_f32 v[42:43], v[42:43], v[166:167]
	v_rcp_f32_e32 v166, v180
	v_rcp_f32_e32 v167, v181
	v_and_b32_e32 v183, 0xffff0000, v237
	v_rcp_f32_e32 v168, v182
	v_rcp_f32_e32 v169, v183
	v_lshlrev_b32_e32 v174, 16, v175
	v_and_b32_e32 v175, 0xffff0000, v175
	v_pk_mul_f32 v[166:167], v[166:167], v[174:175]
	v_lshlrev_b32_e32 v174, 16, v171
	v_pk_mul_f32 v[48:49], v[48:49], v[166:167]
	v_lshlrev_b32_e32 v166, 16, v177
	v_and_b32_e32 v167, 0xffff0000, v177
	v_pk_mul_f32 v[166:167], v[168:169], v[166:167]
	v_lshlrev_b32_e32 v168, 16, v172
	v_pk_mul_f32 v[44:45], v[44:45], v[166:167]
	v_lshlrev_b32_e32 v166, 16, v170
	v_and_b32_e32 v167, 0xffff0000, v170
	v_rcp_f32_e32 v166, v166
	v_rcp_f32_e32 v167, v167
	v_and_b32_e32 v169, 0xffff0000, v172
	v_rcp_f32_e32 v168, v168
	v_rcp_f32_e32 v169, v169
	v_and_b32_e32 v175, 0xffff0000, v171
	v_lshlrev_b32_e32 v170, 16, v162
	v_and_b32_e32 v171, 0xffff0000, v162
	v_pk_mul_f32 v[166:167], v[166:167], v[170:171]
	v_lshlrev_b32_e32 v172, 16, v173
	v_and_b32_e32 v173, 0xffff0000, v173
	v_pk_mul_f32 v[38:39], v[38:39], v[166:167]
	v_lshlrev_b32_e32 v166, 16, v164
	v_and_b32_e32 v167, 0xffff0000, v164
	v_pk_mul_f32 v[166:167], v[168:169], v[166:167]
	v_rcp_f32_e32 v162, v172
	v_lshlrev_b32_e32 v168, 16, v163
	v_and_b32_e32 v169, 0xffff0000, v163
	v_rcp_f32_e32 v163, v173
	v_pk_mul_f32 v[34:35], v[34:35], v[166:167]
	v_rcp_f32_e32 v166, v174
	v_rcp_f32_e32 v167, v175
	v_lshlrev_b32_e32 v164, 16, v165
	v_and_b32_e32 v165, 0xffff0000, v165
	v_pk_mul_f32 v[162:163], v[162:163], v[164:165]
	v_pk_mul_f32 v[166:167], v[166:167], v[168:169]
	v_pk_mul_f32 v[36:37], v[36:37], v[162:163]
	s_waitcnt vmcnt(0)
	v_lshlrev_b32_e32 v162, 16, v158
	v_and_b32_e32 v163, 0xffff0000, v158
	v_lshlrev_b32_e32 v164, 16, v159
	v_and_b32_e32 v165, 0xffff0000, v159
	v_lshlrev_b32_e32 v159, 16, v160
	v_pk_mul_f32 v[40:41], v[40:41], v[166:167]
	v_and_b32_e32 v166, 0xffff0000, v160
	v_rcp_f32_e32 v158, v162
	v_rcp_f32_e32 v160, v159
	v_rcp_f32_e32 v159, v163
	v_lshlrev_b32_e32 v167, 16, v161
	v_and_b32_e32 v168, 0xffff0000, v161
	v_rcp_f32_e32 v161, v166
	v_lshlrev_b32_e32 v162, 16, v154
	v_and_b32_e32 v163, 0xffff0000, v154
	v_pk_mul_f32 v[158:159], v[158:159], v[162:163]
	v_rcp_f32_e32 v154, v167
	v_pk_mul_f32 v[30:31], v[30:31], v[158:159]
	v_lshlrev_b32_e32 v158, 16, v156
	v_and_b32_e32 v159, 0xffff0000, v156
	v_pk_mul_f32 v[158:159], v[160:161], v[158:159]
	v_lshlrev_b32_e32 v160, 16, v155
	v_and_b32_e32 v161, 0xffff0000, v155
	v_rcp_f32_e32 v155, v168
	v_pk_mul_f32 v[26:27], v[26:27], v[158:159]
	v_rcp_f32_e32 v158, v164
	v_rcp_f32_e32 v159, v165
	v_lshlrev_b32_e32 v156, 16, v157
	v_and_b32_e32 v157, 0xffff0000, v157
	v_pk_mul_f32 v[154:155], v[154:155], v[156:157]
	v_pk_mul_f32 v[158:159], v[158:159], v[160:161]
	v_pk_mul_f32 v[28:29], v[28:29], v[154:155]
	v_lshlrev_b32_e32 v154, 16, v150
	v_and_b32_e32 v155, 0xffff0000, v150
	v_lshlrev_b32_e32 v156, 16, v151
	v_and_b32_e32 v157, 0xffff0000, v151
	v_lshlrev_b32_e32 v151, 16, v152
	v_pk_mul_f32 v[32:33], v[32:33], v[158:159]
	v_and_b32_e32 v158, 0xffff0000, v152
	v_rcp_f32_e32 v150, v154
	v_rcp_f32_e32 v152, v151
	v_rcp_f32_e32 v151, v155
	v_lshlrev_b32_e32 v159, 16, v153
	v_and_b32_e32 v160, 0xffff0000, v153
	v_rcp_f32_e32 v153, v158
	v_lshlrev_b32_e32 v154, 16, v146
	v_and_b32_e32 v155, 0xffff0000, v146
	v_pk_mul_f32 v[150:151], v[150:151], v[154:155]
	v_rcp_f32_e32 v146, v159
	v_pk_mul_f32 v[22:23], v[22:23], v[150:151]
	v_lshlrev_b32_e32 v150, 16, v148
	v_and_b32_e32 v151, 0xffff0000, v148
	v_pk_mul_f32 v[150:151], v[152:153], v[150:151]
	v_lshlrev_b32_e32 v152, 16, v147
	v_and_b32_e32 v153, 0xffff0000, v147
	v_rcp_f32_e32 v147, v160
	v_pk_mul_f32 v[18:19], v[18:19], v[150:151]
	v_rcp_f32_e32 v150, v156
	v_rcp_f32_e32 v151, v157
	v_lshlrev_b32_e32 v148, 16, v149
	v_and_b32_e32 v149, 0xffff0000, v149
	v_pk_mul_f32 v[146:147], v[146:147], v[148:149]
	v_pk_mul_f32 v[150:151], v[150:151], v[152:153]
	v_pk_mul_f32 v[20:21], v[20:21], v[146:147]
	v_lshlrev_b32_e32 v146, 16, v142
	v_and_b32_e32 v147, 0xffff0000, v142
	v_lshlrev_b32_e32 v148, 16, v143
	v_and_b32_e32 v149, 0xffff0000, v143
	v_lshlrev_b32_e32 v143, 16, v144
	v_pk_mul_f32 v[24:25], v[24:25], v[150:151]
	v_and_b32_e32 v150, 0xffff0000, v144
	v_rcp_f32_e32 v142, v146
	v_rcp_f32_e32 v144, v143
	v_rcp_f32_e32 v143, v147
	v_lshlrev_b32_e32 v151, 16, v145
	v_and_b32_e32 v152, 0xffff0000, v145
	v_rcp_f32_e32 v145, v150
	v_lshlrev_b32_e32 v146, 16, v138
	v_and_b32_e32 v147, 0xffff0000, v138
	v_pk_mul_f32 v[142:143], v[142:143], v[146:147]
	v_rcp_f32_e32 v138, v151
	v_pk_mul_f32 v[14:15], v[14:15], v[142:143]
	v_lshlrev_b32_e32 v142, 16, v140
	v_and_b32_e32 v143, 0xffff0000, v140
	v_pk_mul_f32 v[142:143], v[144:145], v[142:143]
	v_lshlrev_b32_e32 v144, 16, v139
	v_and_b32_e32 v145, 0xffff0000, v139
	v_rcp_f32_e32 v139, v152
	v_pk_mul_f32 v[10:11], v[10:11], v[142:143]
	v_rcp_f32_e32 v142, v148
	v_rcp_f32_e32 v143, v149
	v_lshlrev_b32_e32 v140, 16, v141
	v_and_b32_e32 v141, 0xffff0000, v141
	v_pk_mul_f32 v[138:139], v[138:139], v[140:141]
	v_pk_mul_f32 v[142:143], v[142:143], v[144:145]
	v_pk_mul_f32 v[12:13], v[12:13], v[138:139]
	v_lshlrev_b32_e32 v138, 16, v134
	v_and_b32_e32 v139, 0xffff0000, v134
	v_lshlrev_b32_e32 v140, 16, v135
	v_and_b32_e32 v141, 0xffff0000, v135
	v_lshlrev_b32_e32 v135, 16, v136
	v_pk_mul_f32 v[16:17], v[16:17], v[142:143]
	v_and_b32_e32 v142, 0xffff0000, v136
	v_rcp_f32_e32 v134, v138
	v_rcp_f32_e32 v136, v135
	v_rcp_f32_e32 v135, v139
	v_lshlrev_b32_e32 v143, 16, v137
	v_and_b32_e32 v144, 0xffff0000, v137
	v_rcp_f32_e32 v137, v142
	v_lshlrev_b32_e32 v138, 16, v130
	v_and_b32_e32 v139, 0xffff0000, v130
	v_pk_mul_f32 v[134:135], v[134:135], v[138:139]
	v_rcp_f32_e32 v130, v143
	v_pk_mul_f32 v[6:7], v[6:7], v[134:135]
	v_lshlrev_b32_e32 v134, 16, v132
	v_and_b32_e32 v135, 0xffff0000, v132
	v_pk_mul_f32 v[134:135], v[136:137], v[134:135]
	v_lshlrev_b32_e32 v136, 16, v131
	v_pk_mul_f32 v[2:3], v[2:3], v[134:135]
	v_rcp_f32_e32 v134, v140
	v_rcp_f32_e32 v135, v141
	v_and_b32_e32 v137, 0xffff0000, v131
	v_rcp_f32_e32 v131, v144
	v_lshlrev_b32_e32 v132, 16, v133
	v_and_b32_e32 v133, 0xffff0000, v133
	v_pk_mul_f32 v[134:135], v[134:135], v[136:137]
	v_pk_mul_f32 v[130:131], v[130:131], v[132:133]
	v_pk_mul_f32 v[8:9], v[8:9], v[134:135]
	v_pk_mul_f32 v[4:5], v[4:5], v[130:131]
	s_branch .LBB0_807
